# v21_2c
# speedup vs baseline: 1.0062x; 1.0062x over previous
; __device__ __forceinline__ float bflo(u32 v) { return __uint_as_float(v << 16); }
; __device__ __forceinline__ float bfhi(u32 v) { return __uint_as_float(v & 0xffff0000u); }
; __device__ __forceinline__ float sigmoidf_(float x) { return 1.f / (1.f + __expf(-x)); }
; __device__ void phase2c(const Params& p) {
;     ...
;     {
;       const int hh = lane >> 3;
;       float l0 = p.LSE[((size_t)0 * NTOK + tok) * 8 + hh];
;       float l1 = p.LSE[((size_t)1 * NTOK + tok) * 8 + hh];
;       float l2 = p.LSE[((size_t)2 * NTOK + tok) * 8 + hh];
;       float mx = fmaxf(l0, fmaxf(l1, l2));
;       float w0 = __expf(l0 - mx), w1 = __expf(l1 - mx), w2 = __expf(l2 - mx);
;       float inv = 1.f / (w0 + w1 + w2);
;       w0 *= inv; w1 *= inv; w2 *= inv;
; #pragma unroll
;       for (int hf = 0; hf < 2; ++hf) {
;         const int col = 16 * lane + 8 * hf;
;         u32x4 o0 = *(const u32x4*)(p.OG + ((size_t)0 * NTOK + tok) * 1024 + col);
;         u32x4 o1 = *(const u32x4*)(p.OG + ((size_t)1 * NTOK + tok) * 1024 + col);
;         u32x4 o2 = *(const u32x4*)(p.OG + ((size_t)2 * NTOK + tok) * 1024 + col);
;         u32x4 zz = *(const u32x4*)(p.PROJ + (size_t)tok * NP + C_AZ + col);
;         u32x4 res;
; #pragma unroll
;         for (int i = 0; i < 4; ++i) {
;           float za = bflo(zz[i]), zb = bfhi(zz[i]);
;           float va = (w0 * bflo(o0[i]) + w1 * bflo(o1[i]) + w2 * bflo(o2[i])) * za * sigmoidf_(za);
;           float vb = (w0 * bfhi(o0[i]) + w1 * bfhi(o1[i]) + w2 * bfhi(o2[i])) * zb * sigmoidf_(zb);
;           res[i] = pack2(va, vb);
;         }
;         *(u32x4*)(p.YA + (size_t)tok * 1024 + col) = res;
.LBB0_513:
	v_ashrrev_i32_e32 v25, 31, v24
	v_lshl_add_u64 v[2:3], v[24:25], 0, s[12:13]
	v_lshlrev_b64 v[4:5], 5, v[2:3]
	v_lshl_add_u64 v[10:11], v[24:25], 0, s[14:15]
	v_lshl_add_u64 v[8:9], v[28:29], 0, v[4:5]
	v_lshlrev_b64 v[4:5], 5, v[10:11]
	v_lshlrev_b64 v[20:21], 11, v[24:25]
	v_lshlrev_b64 v[0:1], 5, v[24:25]
	v_lshl_add_u64 v[12:13], v[28:29], 0, v[4:5]
	v_lshl_add_u64 v[18:19], v[38:39], 0, v[20:21]
	v_lshl_add_u64 v[0:1], v[28:29], 0, v[0:1]
	global_load_dwordx4 v[4:7], v[18:19], off
	global_load_dword v57, v[0:1], off
	global_load_dword v60, v[8:9], off
	global_load_dword v61, v[12:13], off
	v_lshlrev_b64 v[12:13], 15, v[24:25]
	v_lshlrev_b64 v[0:1], 11, v[2:3]
	v_lshlrev_b64 v[2:3], 11, v[10:11]
	v_lshl_add_u64 v[16:17], s[74:75], 0, v[12:13]
	v_lshl_add_u64 v[22:23], v[38:39], 0, v[0:1]
	v_lshl_add_u64 v[46:47], v[38:39], 0, v[2:3]
	v_lshl_add_u64 v[48:49], v[16:17], 0, s[16:17]
	global_load_dwordx4 v[8:11], v[22:23], off
	global_load_dwordx4 v[0:3], v[46:47], off
	v_lshl_add_u64 v[12:13], v[48:49], 0, v[42:43]
	global_load_dwordx4 v[12:15], v[12:13], off
	s_mov_b32 s100, s3
	s_mov_b32 s101, 0
	v_lshlrev_b64 v[228:229], 12, v[24:25]
	v_lshl_add_u64 v[236:237], v[48:49], 0, v[44:45]
	v_lshl_add_u64 v[234:235], v[16:17], 0, v[26:27]
	v_lshl_add_u64 v[230:231], v[30:31], 0, v[228:229]
	v_lshl_add_u64 v[232:233], v[32:33], 0, v[228:229]
	v_lshl_add_u64 v[234:235], v[234:235], 0, s[100:101]
	global_load_dwordx4 v[128:131], v[236:237], off
	global_load_dwordx4 v[132:135], v[22:23], off offset:16
	global_load_dwordx4 v[136:139], v[18:19], off offset:16
	global_load_dwordx4 v[140:143], v[46:47], off offset:16
	global_load_dwordx4 v[144:147], v[230:231], off offset:48
	global_load_dwordx4 v[148:151], v[232:233], off offset:48
	global_load_dwordx4 v[152:155], v[230:231], off
	global_load_dwordx4 v[156:159], v[232:233], off
	global_load_dwordx4 v[160:163], v[234:235], off
	global_load_dwordx4 v[164:167], v[230:231], off offset:32
	global_load_dwordx4 v[168:171], v[230:231], off offset:16
	global_load_dwordx4 v[172:175], v[232:233], off offset:32
	global_load_dwordx4 v[176:179], v[232:233], off offset:16
	global_load_dwordx4 v[180:183], v[34:35], off offset:16
	global_load_dwordx4 v[184:187], v[34:35], off
	global_load_dwordx4 v[192:195], v[234:235], off offset:16
	global_load_dwordx4 v[196:199], v[34:35], off offset:32
	global_load_dwordx4 v[200:203], v[34:35], off offset:48
	global_load_dwordx4 v[204:207], v[234:235], off offset:32
	global_load_dwordx4 v[208:211], v[34:35], off offset:64
	global_load_dwordx4 v[212:215], v[34:35], off offset:80
	global_load_dwordx4 v[216:219], v[234:235], off offset:48
	global_load_dwordx4 v[220:223], v[34:35], off offset:96
	global_load_dwordx4 v[224:227], v[34:35], off offset:112
	s_nop 0
	s_waitcnt vmcnt(24)
	v_and_b32_e32 v51, 0xffff0000, v4
	v_lshlrev_b32_e32 v52, 16, v4
	v_and_b32_e32 v55, 0xffff0000, v5
	s_nop 0
	v_max3_f32 v4, v57, v60, v61
	v_lshlrev_b32_e32 v56, 16, v5
	v_sub_f32_e32 v5, v60, v4
	s_nop 0
	v_lshlrev_b32_e32 v50, 16, v8
	s_nop 0
	v_lshlrev_b32_e32 v58, 16, v0
	v_and_b32_e32 v59, 0xffff0000, v0
	v_sub_f32_e32 v0, v57, v4
	v_and_b32_e32 v53, 0xffff0000, v8
	v_sub_f32_e32 v4, v61, v4
	s_nop 0
	v_lshlrev_b32_e32 v60, 16, v12
	v_and_b32_e32 v61, 0xffff0000, v12
	v_mul_f32_e32 v0, 0x3fb8aa3b, v0
	v_mul_f32_e32 v8, 0x3fb8aa3b, v5
	v_mul_f32_e32 v57, 0x3fb8aa3b, v4
	v_mul_f32_e32 v62, 0xbfb8aa3b, v60
	v_mul_f32_e32 v63, 0xbfb8aa3b, v61
	v_exp_f32_e32 v5, v0
	v_exp_f32_e32 v4, v8
	v_exp_f32_e32 v62, v62
	v_exp_f32_e32 v63, v63
	v_exp_f32_e32 v0, v57
	v_add_f32_e32 v8, v5, v4
	v_lshlrev_b32_e32 v12, 16, v13
	v_pk_add_f32 v[62:63], v[62:63], 1.0 op_sel_hi:[1,0]
	v_add_f32_e32 v8, v0, v8
	v_and_b32_e32 v13, 0xffff0000, v13
	v_mul_f32_e32 v64, 0xbfb8aa3b, v12
	v_mul_f32_e32 v65, 0xbfb8aa3b, v13
	v_exp_f32_e32 v64, v64
	v_exp_f32_e32 v65, v65
	v_rcp_f32_e32 v8, v8
	s_nop 0
	v_pk_add_f32 v[64:65], v[64:65], 1.0 op_sel_hi:[1,0]
	v_pk_mul_f32 v[4:5], v[4:5], v[8:9] op_sel_hi:[1,0]
	s_mov_b64 vcc, s[0:1]
	v_pk_mul_f32 v[52:53], v[4:5], v[52:53] op_sel:[1,0] op_sel_hi:[0,1]
	v_mul_f32_e32 v0, v0, v8
	s_mov_b64 vcc, s[4:5]
	v_pk_fma_f32 v[50:51], v[4:5], v[50:51], v[52:53]
	v_pk_fma_f32 v[50:51], v[0:1], v[58:59], v[50:51] op_sel_hi:[0,1,1]
	v_rcp_f32_e32 v63, v63
	s_nop 0
	v_rcp_f32_e32 v62, v62
	s_nop 0
	v_pk_mul_f32 v[50:51], v[50:51], v[60:61]
	v_lshlrev_b32_e32 v54, 16, v9
	v_pk_mul_f32 v[50:51], v[62:63], v[50:51]
	v_and_b32_e32 v57, 0xffff0000, v9
	v_cvt_pk_bf16_f32 v8, v50, v51
	v_lshlrev_b32_e32 v50, 16, v1
	v_and_b32_e32 v51, 0xffff0000, v1
	v_rcp_f32_e32 v53, v65
	s_nop 0
	v_pk_mul_f32 v[56:57], v[4:5], v[56:57] op_sel:[1,0] op_sel_hi:[0,1]
	s_nop 0
	v_pk_fma_f32 v[54:55], v[4:5], v[54:55], v[56:57]
	v_rcp_f32_e32 v52, v64
	s_nop 0
	v_pk_fma_f32 v[50:51], v[0:1], v[50:51], v[54:55] op_sel_hi:[0,1,1]
	v_pk_mul_f32 v[12:13], v[50:51], v[12:13]
	v_lshlrev_b32_e32 v54, 16, v6
	v_pk_mul_f32 v[12:13], v[52:53], v[12:13]
	v_and_b32_e32 v53, 0xffff0000, v6
	v_cvt_pk_bf16_f32 v9, v12, v13
	v_lshlrev_b32_e32 v12, 16, v14
	v_and_b32_e32 v13, 0xffff0000, v14
	v_mul_f32_e32 v1, 0xbfb8aa3b, v12
	v_exp_f32_e32 v50, v1
	v_mul_f32_e32 v1, 0xbfb8aa3b, v13
	v_exp_f32_e32 v51, v1
	v_lshlrev_b32_e32 v56, 16, v2
	v_and_b32_e32 v57, 0xffff0000, v2
	v_lshlrev_b32_e32 v52, 16, v10
	v_pk_add_f32 v[50:51], v[50:51], 1.0 op_sel_hi:[1,0]
	v_and_b32_e32 v55, 0xffff0000, v10
	v_pk_mul_f32 v[54:55], v[4:5], v[54:55] op_sel:[1,0] op_sel_hi:[0,1]
	v_pk_fma_f32 v[52:53], v[4:5], v[52:53], v[54:55]
	v_rcp_f32_e32 v51, v51
	s_nop 0
	v_pk_fma_f32 v[52:53], v[0:1], v[56:57], v[52:53] op_sel_hi:[0,1,1]
	v_rcp_f32_e32 v50, v50
	s_nop 0
	v_pk_mul_f32 v[12:13], v[52:53], v[12:13]
	v_lshlrev_b32_e32 v14, 16, v11
	v_pk_mul_f32 v[12:13], v[50:51], v[12:13]
	v_lshlrev_b32_e32 v50, 16, v7
	v_cvt_pk_bf16_f32 v10, v12, v13
	v_lshlrev_b32_e32 v12, 16, v15
	v_and_b32_e32 v13, 0xffff0000, v15
	v_mul_f32_e32 v1, 0xbfb8aa3b, v12
	v_exp_f32_e32 v6, v1
	v_mul_f32_e32 v1, 0xbfb8aa3b, v13
	v_and_b32_e32 v15, 0xffff0000, v7
	v_exp_f32_e32 v7, v1
	v_and_b32_e32 v51, 0xffff0000, v11
	v_pk_mul_f32 v[50:51], v[4:5], v[50:51] op_sel:[1,0] op_sel_hi:[0,1]
	v_pk_fma_f32 v[14:15], v[4:5], v[14:15], v[50:51]
	v_pk_add_f32 v[6:7], v[6:7], 1.0 op_sel_hi:[1,0]
	v_lshlrev_b32_e32 v2, 16, v3
	v_and_b32_e32 v3, 0xffff0000, v3
	v_pk_fma_f32 v[2:3], v[0:1], v[2:3], v[14:15] op_sel_hi:[0,1,1]
	v_pk_mul_f32 v[2:3], v[2:3], v[12:13]
	v_rcp_f32_e32 v7, v7
	s_nop 0
	v_lshlrev_b64 v[56:57], 12, v[24:25]
	v_rcp_f32_e32 v6, v6
	s_nop 0
	v_pk_mul_f32 v[2:3], v[6:7], v[2:3]
	v_lshl_add_u64 v[6:7], v[48:49], 0, v[44:45]
	v_cvt_pk_bf16_f32 v11, v2, v3
	v_lshl_add_u64 v[2:3], v[40:41], 0, v[20:21]
	global_store_dwordx4 v[2:3], v[8:11], off
	s_waitcnt vmcnt(21)
; __device__ __forceinline__ float bflo(u32 v) { return __uint_as_float(v << 16); }
; __device__ __forceinline__ float bfhi(u32 v) { return __uint_as_float(v & 0xffff0000u); }
; __device__ __forceinline__ float sigmoidf_(float x) { return 1.f / (1.f + __expf(-x)); }
; __device__ void phase2c(const Params& p) {
;     ...
;       for (int hf = 0; hf < 2; ++hf) {
;         const int col = 16 * lane + 8 * hf;
;         u32x4 o0 = *(const u32x4*)(p.OG + ((size_t)0 * NTOK + tok) * 1024 + col);
;         u32x4 o1 = *(const u32x4*)(p.OG + ((size_t)1 * NTOK + tok) * 1024 + col);
;         u32x4 o2 = *(const u32x4*)(p.OG + ((size_t)2 * NTOK + tok) * 1024 + col);
;         u32x4 zz = *(const u32x4*)(p.PROJ + (size_t)tok * NP + C_AZ + col);
;         u32x4 res;
; #pragma unroll
;         for (int i = 0; i < 4; ++i) {
;           float za = bflo(zz[i]), zb = bfhi(zz[i]);
;           float va = (w0 * bflo(o0[i]) + w1 * bflo(o1[i]) + w2 * bflo(o2[i])) * za * sigmoidf_(za);
;           float vb = (w0 * bfhi(o0[i]) + w1 * bfhi(o1[i]) + w2 * bfhi(o2[i])) * zb * sigmoidf_(zb);
;           res[i] = pack2(va, vb);
;         }
;         *(u32x4*)(p.YA + (size_t)tok * 1024 + col) = res;
;       }
;     }
;     {
;       const int col0 = 32 * lane;
;       f32x4 v[8];
;       float ss = 0.f;
; #pragma unroll
;       for (int i = 0; i < 4; ++i) {
;         u32x4 a = *(const u32x4*)(p.OF + (size_t)tok * 2048 + col0 + 8 * i);
;         u32x4 b = *(const u32x4*)(p.OB + (size_t)tok * 2048 + col0 + 8 * i);
;         v[2 * i] = f32x4{bflo(a[0]) + bflo(b[0]), bfhi(a[0]) + bfhi(b[0]), bflo(a[1]) + bflo(b[1]), bfhi(a[1]) + bfhi(b[1])};
;         v[2 * i + 1] = f32x4{bflo(a[2]) + bflo(b[2]), bfhi(a[2]) + bfhi(b[2]), bflo(a[3]) + bflo(b[3]), bfhi(a[3]) + bfhi(b[3])};
;       }
; #pragma unroll
;       for (int i = 0; i < 8; ++i) ss += v[i][0] * v[i][0] + v[i][1] * v[i][1] + v[i][2] * v[i][2] + v[i][3] * v[i][3];
	s_nop 0
	s_nop 0
	s_nop 0
	v_add_u32_e32 v24, s2, v24
	s_nop 0
	v_lshlrev_b32_e32 v14, 16, v128
	v_and_b32_e32 v15, 0xffff0000, v128
	v_mul_f32_e32 v1, 0xbfb8aa3b, v14
	v_exp_f32_e32 v22, v1
	v_mul_f32_e32 v1, 0xbfb8aa3b, v15
	v_exp_f32_e32 v23, v1
	s_nop 0
	v_lshlrev_b32_e32 v50, 16, v132
	v_and_b32_e32 v53, 0xffff0000, v132
	s_nop 0
	v_lshlrev_b32_e32 v52, 16, v136
	v_pk_add_f32 v[22:23], v[22:23], 1.0 op_sel_hi:[1,0]
	v_and_b32_e32 v51, 0xffff0000, v136
	v_pk_mul_f32 v[52:53], v[4:5], v[52:53] op_sel:[1,0] op_sel_hi:[0,1]
	v_pk_fma_f32 v[50:51], v[4:5], v[50:51], v[52:53]
	s_nop 0
	v_lshlrev_b32_e32 v52, 16, v140
	v_and_b32_e32 v53, 0xffff0000, v140
	v_pk_fma_f32 v[50:51], v[0:1], v[52:53], v[50:51] op_sel_hi:[0,1,1]
	v_rcp_f32_e32 v23, v23
	s_nop 0
	v_pk_mul_f32 v[14:15], v[50:51], v[14:15]
	v_rcp_f32_e32 v22, v22
	s_nop 0
	v_pk_mul_f32 v[14:15], v[14:15], v[22:23]
	v_lshlrev_b32_e32 v22, 16, v133
	v_cvt_pk_bf16_f32 v6, v14, v15
	v_lshlrev_b32_e32 v14, 16, v129
	v_and_b32_e32 v15, 0xffff0000, v129
	v_mul_f32_e32 v1, 0xbfb8aa3b, v14
	v_exp_f32_e32 v10, v1
	v_mul_f32_e32 v1, 0xbfb8aa3b, v15
	v_and_b32_e32 v23, 0xffff0000, v137
	v_lshlrev_b32_e32 v18, 16, v137
	v_and_b32_e32 v19, 0xffff0000, v133
	v_exp_f32_e32 v11, v1
	v_pk_mul_f32 v[18:19], v[4:5], v[18:19] op_sel:[1,0] op_sel_hi:[0,1]
	v_pk_fma_f32 v[18:19], v[4:5], v[22:23], v[18:19]
	v_lshlrev_b32_e32 v22, 16, v141
	v_pk_add_f32 v[10:11], v[10:11], 1.0 op_sel_hi:[1,0]
	v_and_b32_e32 v23, 0xffff0000, v141
	v_pk_fma_f32 v[18:19], v[0:1], v[22:23], v[18:19] op_sel_hi:[0,1,1]
	v_pk_mul_f32 v[14:15], v[18:19], v[14:15]
	v_and_b32_e32 v23, 0xffff0000, v134
	v_rcp_f32_e32 v11, v11
	s_nop 0
	v_rcp_f32_e32 v10, v10
	s_nop 0
	v_pk_mul_f32 v[10:11], v[14:15], v[10:11]
	v_lshlrev_b32_e32 v22, 16, v138
	v_cvt_pk_bf16_f32 v7, v10, v11
	v_lshlrev_b32_e32 v10, 16, v130
	v_and_b32_e32 v11, 0xffff0000, v130
	v_mul_f32_e32 v1, 0xbfb8aa3b, v10
	v_exp_f32_e32 v14, v1
	v_mul_f32_e32 v1, 0xbfb8aa3b, v11
	v_exp_f32_e32 v15, v1
	v_lshlrev_b32_e32 v18, 16, v134
	v_and_b32_e32 v19, 0xffff0000, v138
	v_pk_mul_f32 v[22:23], v[4:5], v[22:23] op_sel:[1,0] op_sel_hi:[0,1]
	v_pk_add_f32 v[14:15], v[14:15], 1.0 op_sel_hi:[1,0]
	v_pk_fma_f32 v[18:19], v[4:5], v[18:19], v[22:23]
	v_lshlrev_b32_e32 v22, 16, v142
	v_and_b32_e32 v23, 0xffff0000, v142
	v_pk_fma_f32 v[18:19], v[0:1], v[22:23], v[18:19] op_sel_hi:[0,1,1]
	v_pk_mul_f32 v[10:11], v[18:19], v[10:11]
	v_rcp_f32_e32 v15, v15
	s_nop 0
	v_rcp_f32_e32 v14, v14
	s_nop 0
	v_pk_mul_f32 v[10:11], v[10:11], v[14:15]
	v_lshlrev_b32_e32 v14, 16, v135
	v_cvt_pk_bf16_f32 v8, v10, v11
	v_lshlrev_b32_e32 v10, 16, v131
	v_and_b32_e32 v11, 0xffff0000, v131
	v_mul_f32_e32 v1, 0xbfb8aa3b, v10
	v_exp_f32_e32 v12, v1
	v_mul_f32_e32 v1, 0xbfb8aa3b, v11
	v_and_b32_e32 v19, 0xffff0000, v135
	v_exp_f32_e32 v13, v1
	v_lshlrev_b32_e32 v18, 16, v139
	v_and_b32_e32 v15, 0xffff0000, v139
	v_pk_mul_f32 v[18:19], v[4:5], v[18:19] op_sel:[1,0] op_sel_hi:[0,1]
	v_pk_add_f32 v[12:13], v[12:13], 1.0 op_sel_hi:[1,0]
	v_pk_fma_f32 v[4:5], v[4:5], v[14:15], v[18:19]
	v_lshlrev_b32_e32 v14, 16, v143
	v_and_b32_e32 v15, 0xffff0000, v143
	v_pk_fma_f32 v[0:1], v[0:1], v[14:15], v[4:5] op_sel_hi:[0,1,1]
	v_pk_mul_f32 v[0:1], v[0:1], v[10:11]
	v_rcp_f32_e32 v5, v13
	s_nop 0
	v_lshl_add_u64 v[18:19], v[32:33], 0, v[56:57]
	v_rcp_f32_e32 v4, v12
	s_nop 0
	v_pk_mul_f32 v[0:1], v[0:1], v[4:5]
	v_lshl_add_u64 v[10:11], v[16:17], 0, v[26:27]
	v_cvt_pk_bf16_f32 v9, v0, v1
	global_store_dwordx4 v[2:3], v[6:9], off offset:16
	s_waitcnt vmcnt(11)
	v_add_co_u32_e32 v54, vcc, s3, v10
	s_nop 0
	v_lshl_add_u64 v[8:9], v[30:31], 0, v[56:57]
	v_addc_co_u32_e32 v55, vcc, 0, v11, vcc
	s_nop 0
	s_nop 0
	s_nop 0
	v_lshlrev_b32_e32 v49, 16, v148
	s_nop 0
	v_lshlrev_b32_e32 v58, 16, v155
	v_and_b32_e32 v59, 0xffff0000, v155
	s_nop 0
	v_lshlrev_b32_e32 v60, 16, v159
	v_and_b32_e32 v61, 0xffff0000, v159
	v_pk_add_f32 v[58:59], v[58:59], v[60:61]
	s_nop 0
	v_lshlrev_b32_e32 v60, 16, v162
	v_and_b32_e32 v61, 0xffff0000, v162
	v_mul_f32_e32 v25, 0xbfb8aa3b, v60
	v_exp_f32_e32 v62, v25
	v_mul_f32_e32 v25, 0xbfb8aa3b, v61
	v_exp_f32_e32 v63, v25
	v_lshlrev_b32_e32 v72, 16, v154
	v_and_b32_e32 v73, 0xffff0000, v154
	v_lshlrev_b32_e32 v68, 16, v158
	v_pk_add_f32 v[76:77], v[62:63], 1.0 op_sel_hi:[1,0]
	v_and_b32_e32 v69, 0xffff0000, v158
	v_pk_add_f32 v[62:63], v[72:73], v[68:69]
	v_and_b32_e32 v79, 0xffff0000, v153
	v_lshlrev_b32_e32 v80, 16, v157
	v_rcp_f32_e32 v69, v77
	s_nop 0
	v_lshlrev_b32_e32 v78, 16, v153
	v_lshlrev_b32_e32 v72, 16, v161
	v_rcp_f32_e32 v68, v76
	s_nop 0
	v_and_b32_e32 v73, 0xffff0000, v161
	v_mul_f32_e32 v25, 0xbfb8aa3b, v72
	v_exp_f32_e32 v76, v25
	v_mul_f32_e32 v25, 0xbfb8aa3b, v73
	v_exp_f32_e32 v77, v25
	v_and_b32_e32 v81, 0xffff0000, v157
	v_lshlrev_b32_e32 v47, 16, v144
	v_lshlrev_b32_e32 v46, 16, v146
	v_pk_add_f32 v[90:91], v[76:77], 1.0 op_sel_hi:[1,0]
	v_pk_add_f32 v[76:77], v[78:79], v[80:81]
	v_lshlrev_b32_e32 v48, 16, v150
	v_pk_add_f32 v[50:51], v[46:47], v[48:49]
	v_and_b32_e32 v47, 0xffff0000, v144
	v_rcp_f32_e32 v79, v91
	s_nop 0
	v_and_b32_e32 v46, 0xffff0000, v146
	v_lshlrev_b32_e32 v80, 16, v160
	v_rcp_f32_e32 v78, v90
	s_nop 0
	v_and_b32_e32 v81, 0xffff0000, v160
	v_mul_f32_e32 v25, 0xbfb8aa3b, v80
	v_exp_f32_e32 v90, v25
	v_mul_f32_e32 v25, 0xbfb8aa3b, v81
	v_and_b32_e32 v49, 0xffff0000, v148
	v_and_b32_e32 v48, 0xffff0000, v150
	v_exp_f32_e32 v91, v25
	v_pk_add_f32 v[52:53], v[46:47], v[48:49]
	v_lshlrev_b32_e32 v47, 16, v145
	v_lshlrev_b32_e32 v46, 16, v147
	v_lshlrev_b32_e32 v49, 16, v149
	v_lshlrev_b32_e32 v48, 16, v151
	v_and_b32_e32 v1, 0xffff0000, v145
	v_and_b32_e32 v0, 0xffff0000, v147
; __device__ __forceinline__ float bflo(u32 v) { return __uint_as_float(v << 16); }
; __device__ __forceinline__ float bfhi(u32 v) { return __uint_as_float(v & 0xffff0000u); }
; __device__ __forceinline__ float sigmoidf_(float x) { return 1.f / (1.f + __expf(-x)); }
; __device__ void phase2c(const Params& p) {
;     ...
;       for (int i = 0; i < 8; ++i) ss += v[i][0] * v[i][0] + v[i][1] * v[i][1] + v[i][2] * v[i][2] + v[i][3] * v[i][3];
;       ss += __shfl_xor(ss, 1);
;       ss += __shfl_xor(ss, 2);
;       ss += __shfl_xor(ss, 4);
;       ss += __shfl_xor(ss, 8);
;       const float r = rsqrtf(ss * (1.f / 512.f) + EPS);
; #pragma unroll
;       for (int i = 0; i < 4; ++i) {
;         u32x4 zz = *(const u32x4*)(p.PROJ + (size_t)tok * NP + C_GZ + col0 + 8 * i);
;         f32x4 g0 = *(const f32x4*)(p.gla_g + ((col0 + 8 * i) & 511));
;         f32x4 g1 = *(const f32x4*)(p.gla_g + ((col0 + 8 * i + 4) & 511));
;         u32x4 res;
; #pragma unroll
;         for (int q = 0; q < 4; ++q) {
;           float za = bflo(zz[q]), zb = bfhi(zz[q]);
;           float ga = (q < 2) ? g0[2 * q] : g1[2 * q - 4];
;           float gb = (q < 2) ? g0[2 * q + 1] : g1[2 * q - 3];
;           float xa = (q < 2) ? v[2 * i][2 * q] : v[2 * i + 1][2 * q - 4];
;           float xb = (q < 2) ? v[2 * i][2 * q + 1] : v[2 * i + 1][2 * q - 3];
;           res[q] = pack2(xa * r * ga * za * sigmoidf_(za), xb * r * gb * zb * sigmoidf_(zb));
;         }
;         *(u32x4*)(p.YB + (size_t)tok * 2048 + col0 + 8 * i) = res;
	v_and_b32_e32 v3, 0xffff0000, v149
	v_and_b32_e32 v2, 0xffff0000, v151
	v_pk_add_f32 v[46:47], v[46:47], v[48:49]
	v_pk_add_f32 v[48:49], v[0:1], v[2:3]
	v_pk_mul_f32 v[0:1], v[52:53], v[52:53]
	v_pk_add_f32 v[90:91], v[90:91], 1.0 op_sel_hi:[1,0]
	v_pk_fma_f32 v[0:1], v[50:51], v[50:51], v[0:1]
	v_pk_fma_f32 v[0:1], v[46:47], v[46:47], v[0:1]
	v_pk_fma_f32 v[64:65], v[48:49], v[48:49], v[0:1]
	v_lshlrev_b32_e32 v92, 16, v152
	v_and_b32_e32 v93, 0xffff0000, v152
	v_lshlrev_b32_e32 v66, 16, v156
	v_and_b32_e32 v67, 0xffff0000, v156
	v_pk_add_f32 v[88:89], v[92:93], v[66:67]
	v_rcp_f32_e32 v91, v91
	s_nop 0
	v_lshlrev_b32_e32 v94, 16, v163
	v_and_b32_e32 v95, 0xffff0000, v163
	v_mul_f32_e32 v66, 0xbfb8aa3b, v94
	v_mul_f32_e32 v67, 0xbfb8aa3b, v95
	v_exp_f32_e32 v66, v66
	v_exp_f32_e32 v67, v67
	s_nop 0
	v_pk_add_f32 v[98:99], v[66:67], 1.0 op_sel_hi:[1,0]
	s_nop 0
	v_lshlrev_b32_e32 v66, 16, v171
	v_and_b32_e32 v67, 0xffff0000, v171
	s_nop 0
	v_lshlrev_b32_e32 v100, 16, v179
	v_and_b32_e32 v101, 0xffff0000, v179
	v_pk_add_f32 v[66:67], v[66:67], v[100:101]
	v_lshlrev_b32_e32 v100, 16, v170
	v_and_b32_e32 v101, 0xffff0000, v170
	v_lshlrev_b32_e32 v22, 16, v178
	v_and_b32_e32 v23, 0xffff0000, v178
	v_pk_add_f32 v[22:23], v[100:101], v[22:23]
	v_lshlrev_b32_e32 v18, 16, v169
	v_and_b32_e32 v19, 0xffff0000, v169
	v_lshlrev_b32_e32 v100, 16, v177
	v_and_b32_e32 v101, 0xffff0000, v177
	v_pk_add_f32 v[100:101], v[18:19], v[100:101]
	v_lshlrev_b32_e32 v18, 16, v168
	v_and_b32_e32 v19, 0xffff0000, v168
	v_lshlrev_b32_e32 v20, 16, v176
	v_and_b32_e32 v21, 0xffff0000, v176
	v_pk_add_f32 v[20:21], v[18:19], v[20:21]
	v_mov_b32_e32 v104, v23
	v_mov_b32_e32 v105, v21
	v_mov_b32_e32 v102, v22
	v_mov_b32_e32 v103, v20
	v_pk_mul_f32 v[104:105], v[104:105], v[104:105]
	v_mov_b32_e32 v16, v66
	v_mov_b32_e32 v17, v100
	v_pk_fma_f32 v[102:103], v[102:103], v[102:103], v[104:105]
	v_mov_b32_e32 v18, v67
	v_mov_b32_e32 v19, v101
	v_pk_fma_f32 v[16:17], v[16:17], v[16:17], v[102:103]
	v_pk_mul_f32 v[74:75], v[62:63], v[62:63]
	v_pk_fma_f32 v[102:103], v[18:19], v[18:19], v[16:17]
	v_lshlrev_b32_e32 v16, 16, v167
	v_and_b32_e32 v17, 0xffff0000, v167
	v_lshlrev_b32_e32 v18, 16, v175
	v_and_b32_e32 v19, 0xffff0000, v175
	v_pk_add_f32 v[16:17], v[16:17], v[18:19]
	v_lshlrev_b32_e32 v18, 16, v166
	v_and_b32_e32 v19, 0xffff0000, v166
	v_lshlrev_b32_e32 v14, 16, v174
	v_and_b32_e32 v15, 0xffff0000, v174
	v_pk_add_f32 v[14:15], v[18:19], v[14:15]
	v_lshlrev_b32_e32 v10, 16, v165
	v_and_b32_e32 v11, 0xffff0000, v165
	v_lshlrev_b32_e32 v18, 16, v173
	v_and_b32_e32 v19, 0xffff0000, v173
	v_pk_add_f32 v[18:19], v[10:11], v[18:19]
	v_lshlrev_b32_e32 v10, 16, v164
	v_and_b32_e32 v11, 0xffff0000, v164
	v_lshlrev_b32_e32 v12, 16, v172
	v_and_b32_e32 v13, 0xffff0000, v172
	v_pk_add_f32 v[12:13], v[10:11], v[12:13]
	v_mov_b32_e32 v106, v15
	v_mov_b32_e32 v107, v13
	v_mov_b32_e32 v104, v14
	v_mov_b32_e32 v105, v12
	v_pk_mul_f32 v[106:107], v[106:107], v[106:107]
	v_mov_b32_e32 v8, v16
	v_mov_b32_e32 v9, v18
	v_pk_fma_f32 v[104:105], v[104:105], v[104:105], v[106:107]
	v_pk_mul_f32 v[92:93], v[88:89], v[88:89]
	v_mov_b32_e32 v10, v17
	v_mov_b32_e32 v11, v19
	v_pk_fma_f32 v[8:9], v[8:9], v[8:9], v[104:105]
	v_pk_mul_f32 v[70:71], v[58:59], v[58:59]
	v_pk_mul_f32 v[96:97], v[76:77], v[76:77]
	v_pk_fma_f32 v[8:9], v[10:11], v[10:11], v[8:9]
	v_add_f32_e32 v10, v74, v75
	v_add_f32_e32 v11, v92, v93
	v_add_f32_e32 v10, v70, v10
	v_add_f32_e32 v11, v96, v11
	v_add_f32_e32 v10, v71, v10
	v_add_f32_e32 v11, v97, v11
	v_add_f32_e32 v10, v11, v10
	v_add_f32_e32 v10, v10, v103
	v_add_f32_e32 v10, v102, v10
	v_add_f32_e32 v9, v10, v9
	v_add_f32_e32 v8, v8, v9
	v_add_f32_e32 v8, v8, v65
	v_add_f32_e32 v8, v64, v8
	ds_bpermute_b32 v9, v82, v8
	v_rcp_f32_e32 v90, v90
	s_nop 0
	s_waitcnt lgkmcnt(0)
	v_add_f32_e32 v8, v8, v9
	ds_bpermute_b32 v9, v83, v8
	s_waitcnt lgkmcnt(0)
	v_add_f32_e32 v8, v8, v9
	ds_bpermute_b32 v9, v84, v8
	s_waitcnt lgkmcnt(0)
	v_add_f32_e32 v8, v8, v9
	ds_bpermute_b32 v9, v85, v8
	v_rcp_f32_e32 v65, v99
	s_nop 0
	s_waitcnt lgkmcnt(0)
	v_add_f32_e32 v8, v8, v9
	v_fmamk_f32 v8, v8, 0x3b000000, v86
	v_mul_f32_e32 v9, 0x4b800000, v8
	v_cmp_gt_f32_e64 s[0:1], s11, v8
	s_nop 1
	v_cndmask_b32_e64 v8, v8, v9, s[0:1]
	v_rsq_f32_e32 v11, v8
	v_rcp_f32_e32 v64, v98
	s_nop 0
	v_lshl_add_u64 v[8:9], v[36:37], 0, v[56:57]
	v_mul_f32_e32 v10, 0x45800000, v11
	v_cndmask_b32_e64 v10, v11, v10, s[0:1]
	v_pk_mul_f32 v[56:57], v[88:89], v[10:11] op_sel_hi:[1,0]
	s_nop 0
	v_pk_mul_f32 v[4:5], v[184:185], v[56:57]
	v_pk_mul_f32 v[56:57], v[76:77], v[10:11] op_sel_hi:[1,0]
	v_pk_mul_f32 v[4:5], v[4:5], v[80:81]
	v_pk_mul_f32 v[6:7], v[186:187], v[56:57]
	v_pk_mul_f32 v[4:5], v[90:91], v[4:5]
	v_pk_mul_f32 v[6:7], v[6:7], v[72:73]
	v_cvt_pk_bf16_f32 v4, v4, v5
	v_pk_mul_f32 v[6:7], v[78:79], v[6:7]
	s_nop 0
	v_cvt_pk_bf16_f32 v5, v6, v7
	v_pk_mul_f32 v[6:7], v[62:63], v[10:11] op_sel_hi:[1,0]
	s_nop 0
	v_pk_mul_f32 v[0:1], v[180:181], v[6:7]
	s_nop 0
	v_pk_mul_f32 v[0:1], v[0:1], v[60:61]
	s_nop 0
	v_pk_mul_f32 v[0:1], v[68:69], v[0:1]
	s_nop 0
	v_cvt_pk_bf16_f32 v6, v0, v1
	v_pk_mul_f32 v[0:1], v[58:59], v[10:11] op_sel_hi:[1,0]
	s_nop 0
	v_pk_mul_f32 v[0:1], v[182:183], v[0:1]
	s_nop 0
	v_pk_mul_f32 v[0:1], v[0:1], v[94:95]
	s_nop 0
	v_pk_mul_f32 v[0:1], v[64:65], v[0:1]
	s_nop 0
	v_cvt_pk_bf16_f32 v7, v0, v1
	global_store_dwordx4 v[8:9], v[4:7], off
	s_waitcnt vmcnt(9)
; __device__ __forceinline__ float bflo(u32 v) { return __uint_as_float(v << 16); }
; __device__ __forceinline__ float bfhi(u32 v) { return __uint_as_float(v & 0xffff0000u); }
; __device__ __forceinline__ float sigmoidf_(float x) { return 1.f / (1.f + __expf(-x)); }
; __device__ void phase2c(const Params& p) {
;     ...
; #pragma unroll
;       for (int i = 0; i < 4; ++i) {
;         u32x4 zz = *(const u32x4*)(p.PROJ + (size_t)tok * NP + C_GZ + col0 + 8 * i);
;         f32x4 g0 = *(const f32x4*)(p.gla_g + ((col0 + 8 * i) & 511));
;         f32x4 g1 = *(const f32x4*)(p.gla_g + ((col0 + 8 * i + 4) & 511));
;         u32x4 res;
; #pragma unroll
;         for (int q = 0; q < 4; ++q) {
;           float za = bflo(zz[q]), zb = bfhi(zz[q]);
;           float ga = (q < 2) ? g0[2 * q] : g1[2 * q - 4];
;           float gb = (q < 2) ? g0[2 * q + 1] : g1[2 * q - 3];
;           float xa = (q < 2) ? v[2 * i][2 * q] : v[2 * i + 1][2 * q - 4];
;           float xb = (q < 2) ? v[2 * i][2 * q + 1] : v[2 * i + 1][2 * q - 3];
;           res[q] = pack2(xa * r * ga * za * sigmoidf_(za), xb * r * gb * zb * sigmoidf_(zb));
;         }
;         *(u32x4*)(p.YB + (size_t)tok * 2048 + col0 + 8 * i) = res;
	s_nop 0
	s_nop 0
	v_lshlrev_b32_e32 v60, 16, v192
	v_and_b32_e32 v61, 0xffff0000, v192
	v_mul_f32_e32 v0, 0xbfb8aa3b, v60
	v_exp_f32_e32 v62, v0
	v_mul_f32_e32 v0, 0xbfb8aa3b, v61
	v_exp_f32_e32 v63, v0
	s_nop 0
	v_pk_add_f32 v[62:63], v[62:63], 1.0 op_sel_hi:[1,0]
	s_nop 0
	s_nop 0
	v_pk_mul_f32 v[20:21], v[20:21], v[10:11] op_sel_hi:[1,0]
	s_nop 0
	v_pk_mul_f32 v[4:5], v[196:197], v[20:21]
	v_rcp_f32_e32 v21, v63
	s_nop 0
	v_pk_mul_f32 v[4:5], v[4:5], v[60:61]
	v_lshlrev_b32_e32 v60, 16, v193
	v_and_b32_e32 v61, 0xffff0000, v193
	v_mul_f32_e32 v1, 0xbfb8aa3b, v60
	v_exp_f32_e32 v64, v1
	v_mul_f32_e32 v1, 0xbfb8aa3b, v61
	v_exp_f32_e32 v65, v1
	v_rcp_f32_e32 v20, v62
	s_nop 0
	v_pk_mul_f32 v[0:1], v[20:21], v[4:5]
	v_pk_add_f32 v[4:5], v[64:65], 1.0 op_sel_hi:[1,0]
	v_cvt_pk_bf16_f32 v0, v0, v1
	s_nop 0
	v_pk_mul_f32 v[20:21], v[100:101], v[10:11] op_sel_hi:[1,0]
	s_nop 0
	v_pk_mul_f32 v[6:7], v[198:199], v[20:21]
	v_rcp_f32_e32 v5, v5
	s_nop 0
	v_pk_mul_f32 v[6:7], v[6:7], v[60:61]
	v_lshlrev_b32_e32 v20, 16, v194
	v_and_b32_e32 v21, 0xffff0000, v194
	v_mul_f32_e32 v2, 0xbfb8aa3b, v20
	v_exp_f32_e32 v60, v2
	v_mul_f32_e32 v2, 0xbfb8aa3b, v21
	v_exp_f32_e32 v61, v2
	v_rcp_f32_e32 v4, v4
	s_nop 0
	v_pk_mul_f32 v[4:5], v[4:5], v[6:7]
	s_nop 0
	v_cvt_pk_bf16_f32 v1, v4, v5
	v_pk_add_f32 v[4:5], v[60:61], 1.0 op_sel_hi:[1,0]
	s_nop 0
	s_nop 0
	v_pk_mul_f32 v[6:7], v[22:23], v[10:11] op_sel_hi:[1,0]
	s_nop 0
	v_pk_mul_f32 v[6:7], v[200:201], v[6:7]
	s_nop 0
	v_pk_mul_f32 v[6:7], v[6:7], v[20:21]
	v_rcp_f32_e32 v5, v5
	s_nop 0
	v_lshlrev_b32_e32 v20, 16, v195
	v_and_b32_e32 v21, 0xffff0000, v195
	v_mul_f32_e32 v3, 0xbfb8aa3b, v20
	v_exp_f32_e32 v22, v3
	v_mul_f32_e32 v3, 0xbfb8aa3b, v21
	v_exp_f32_e32 v23, v3
	v_rcp_f32_e32 v4, v4
	s_nop 0
	v_pk_mul_f32 v[2:3], v[4:5], v[6:7]
	v_pk_add_f32 v[4:5], v[22:23], 1.0 op_sel_hi:[1,0]
	v_cvt_pk_bf16_f32 v2, v2, v3
	s_nop 0
	v_pk_mul_f32 v[6:7], v[66:67], v[10:11] op_sel_hi:[1,0]
	s_nop 0
	v_pk_mul_f32 v[6:7], v[202:203], v[6:7]
	s_nop 0
	v_pk_mul_f32 v[6:7], v[6:7], v[20:21]
	v_rcp_f32_e32 v5, v5
	s_nop 0
	v_rcp_f32_e32 v4, v4
	s_nop 0
	v_pk_mul_f32 v[4:5], v[4:5], v[6:7]
	s_nop 0
	v_cvt_pk_bf16_f32 v3, v4, v5
	global_store_dwordx4 v[8:9], v[0:3], off offset:16
	s_waitcnt vmcnt(7)
	s_nop 0
	s_nop 0
	v_lshlrev_b32_e32 v56, 16, v204
	v_and_b32_e32 v57, 0xffff0000, v204
	v_mul_f32_e32 v0, 0xbfb8aa3b, v56
	v_exp_f32_e32 v58, v0
	v_mul_f32_e32 v0, 0xbfb8aa3b, v57
	v_exp_f32_e32 v59, v0
	s_nop 0
	v_pk_add_f32 v[58:59], v[58:59], 1.0 op_sel_hi:[1,0]
	s_nop 0
	s_nop 0
	v_pk_mul_f32 v[12:13], v[12:13], v[10:11] op_sel_hi:[1,0]
	s_nop 0
	v_pk_mul_f32 v[4:5], v[208:209], v[12:13]
	v_rcp_f32_e32 v13, v59
	s_nop 0
	v_pk_mul_f32 v[4:5], v[4:5], v[56:57]
	v_lshlrev_b32_e32 v56, 16, v205
	v_and_b32_e32 v57, 0xffff0000, v205
	v_mul_f32_e32 v1, 0xbfb8aa3b, v56
	v_exp_f32_e32 v60, v1
	v_mul_f32_e32 v1, 0xbfb8aa3b, v57
	v_exp_f32_e32 v61, v1
	v_rcp_f32_e32 v12, v58
	s_nop 0
	v_pk_mul_f32 v[0:1], v[12:13], v[4:5]
	v_pk_add_f32 v[4:5], v[60:61], 1.0 op_sel_hi:[1,0]
	v_cvt_pk_bf16_f32 v0, v0, v1
	s_nop 0
	v_pk_mul_f32 v[12:13], v[18:19], v[10:11] op_sel_hi:[1,0]
	s_nop 0
	v_pk_mul_f32 v[6:7], v[210:211], v[12:13]
	v_rcp_f32_e32 v5, v5
	s_nop 0
	v_pk_mul_f32 v[6:7], v[6:7], v[56:57]
	v_lshlrev_b32_e32 v12, 16, v206
	v_and_b32_e32 v13, 0xffff0000, v206
	v_mul_f32_e32 v2, 0xbfb8aa3b, v12
	v_exp_f32_e32 v18, v2
	v_mul_f32_e32 v2, 0xbfb8aa3b, v13
	v_exp_f32_e32 v19, v2
	v_rcp_f32_e32 v4, v4
	s_nop 0
	v_pk_mul_f32 v[4:5], v[4:5], v[6:7]
	s_nop 0
	v_cvt_pk_bf16_f32 v1, v4, v5
	v_pk_add_f32 v[4:5], v[18:19], 1.0 op_sel_hi:[1,0]
	s_nop 0
	s_nop 0
	v_pk_mul_f32 v[6:7], v[14:15], v[10:11] op_sel_hi:[1,0]
	s_nop 0
	v_pk_mul_f32 v[6:7], v[212:213], v[6:7]
	v_mov_b32_e32 v20, v51
	v_pk_mul_f32 v[6:7], v[6:7], v[12:13]
	v_rcp_f32_e32 v5, v5
	s_nop 0
	v_mov_b32_e32 v21, v53
	v_lshlrev_b32_e32 v12, 16, v207
	v_and_b32_e32 v13, 0xffff0000, v207
	v_mul_f32_e32 v3, 0xbfb8aa3b, v12
	v_exp_f32_e32 v14, v3
	v_mul_f32_e32 v3, 0xbfb8aa3b, v13
	v_exp_f32_e32 v15, v3
	v_rcp_f32_e32 v4, v4
	s_nop 0
	v_pk_mul_f32 v[2:3], v[4:5], v[6:7]
	v_mov_b32_e32 v51, v52
	v_pk_add_f32 v[4:5], v[14:15], 1.0 op_sel_hi:[1,0]
	v_cvt_pk_bf16_f32 v2, v2, v3
	s_nop 0
	v_pk_mul_f32 v[6:7], v[16:17], v[10:11] op_sel_hi:[1,0]
	s_nop 0
	v_pk_mul_f32 v[6:7], v[214:215], v[6:7]
	s_nop 0
	v_pk_mul_f32 v[6:7], v[6:7], v[12:13]
	v_rcp_f32_e32 v5, v5
	s_nop 0
	v_rcp_f32_e32 v4, v4
	s_nop 0
	v_pk_mul_f32 v[4:5], v[4:5], v[6:7]
	s_nop 0
	v_cvt_pk_bf16_f32 v3, v4, v5
	global_store_dwordx4 v[8:9], v[0:3], off offset:32
	s_waitcnt vmcnt(5)
	s_nop 0
	s_nop 0
	v_lshlrev_b32_e32 v16, 16, v216
	v_and_b32_e32 v17, 0xffff0000, v216
	v_mul_f32_e32 v0, 0xbfb8aa3b, v16
	v_exp_f32_e32 v18, v0
	v_mul_f32_e32 v0, 0xbfb8aa3b, v17
	v_exp_f32_e32 v19, v0
	s_nop 0
	v_pk_add_f32 v[18:19], v[18:19], 1.0 op_sel_hi:[1,0]
	s_nop 0
	s_nop 0
	v_pk_mul_f32 v[20:21], v[20:21], v[10:11] op_sel_hi:[1,0]
	s_nop 0
	v_pk_mul_f32 v[4:5], v[220:221], v[20:21]
	s_nop 0
	v_pk_mul_f32 v[4:5], v[4:5], v[16:17]
	v_rcp_f32_e32 v17, v19
	s_nop 0
	v_rcp_f32_e32 v16, v18
	s_nop 0
	v_pk_mul_f32 v[4:5], v[16:17], v[4:5]
	v_lshlrev_b32_e32 v16, 16, v217
	v_and_b32_e32 v17, 0xffff0000, v217
	v_mul_f32_e32 v0, 0xbfb8aa3b, v16
	v_exp_f32_e32 v18, v0
	v_mul_f32_e32 v0, 0xbfb8aa3b, v17
	v_exp_f32_e32 v19, v0
	v_cvt_pk_bf16_f32 v0, v4, v5
	v_mov_b32_e32 v4, v47
	v_mov_b32_e32 v5, v49
	v_pk_add_f32 v[18:19], v[18:19], 1.0 op_sel_hi:[1,0]
	v_mov_b32_e32 v47, v48
	s_nop 0
	v_pk_mul_f32 v[4:5], v[4:5], v[10:11] op_sel_hi:[1,0]
	s_nop 0
	v_pk_mul_f32 v[4:5], v[222:223], v[4:5]
	v_pk_mul_f32 v[4:5], v[4:5], v[16:17]
	v_rcp_f32_e32 v7, v19
	s_nop 0
	v_lshlrev_b32_e32 v16, 16, v218
	v_rcp_f32_e32 v6, v18
	s_nop 0
	v_and_b32_e32 v17, 0xffff0000, v218
	v_mul_f32_e32 v1, 0xbfb8aa3b, v16
	v_exp_f32_e32 v18, v1
	v_mul_f32_e32 v1, 0xbfb8aa3b, v17
	v_exp_f32_e32 v19, v1
	v_pk_mul_f32 v[4:5], v[6:7], v[4:5]
	s_nop 0
	v_cvt_pk_bf16_f32 v1, v4, v5
	v_pk_add_f32 v[4:5], v[18:19], 1.0 op_sel_hi:[1,0]
	s_nop 0
	s_nop 0
	v_pk_mul_f32 v[6:7], v[50:51], v[10:11] op_sel_hi:[1,0]
	s_nop 0
	v_pk_mul_f32 v[6:7], v[224:225], v[6:7]
	v_pk_mul_f32 v[6:7], v[6:7], v[16:17]
	v_rcp_f32_e32 v5, v5
	s_nop 0
	v_lshlrev_b32_e32 v12, 16, v219
	v_rcp_f32_e32 v4, v4
	s_nop 0
	v_and_b32_e32 v13, 0xffff0000, v219
	v_mul_f32_e32 v2, 0xbfb8aa3b, v12
	v_exp_f32_e32 v16, v2
	v_mul_f32_e32 v2, 0xbfb8aa3b, v13
	v_exp_f32_e32 v17, v2
	v_pk_mul_f32 v[2:3], v[4:5], v[6:7]
	v_pk_add_f32 v[4:5], v[16:17], 1.0 op_sel_hi:[1,0]
	v_cvt_pk_bf16_f32 v2, v2, v3
	s_nop 0
	v_pk_mul_f32 v[6:7], v[46:47], v[10:11] op_sel_hi:[1,0]
	v_pk_mul_f32 v[6:7], v[226:227], v[6:7]
	v_pk_mul_f32 v[6:7], v[6:7], v[12:13]
	v_rcp_f32_e32 v5, v5
	s_nop 0
	v_rcp_f32_e32 v4, v4
	s_nop 0
	v_pk_mul_f32 v[4:5], v[4:5], v[6:7]
	v_cmp_lt_i32_e32 vcc, s18, v24
	v_cvt_pk_bf16_f32 v3, v4, v5
	s_or_b64 s[8:9], vcc, s[8:9]
	global_store_dwordx4 v[8:9], v[0:3], off offset:48
	s_andn2_b64 exec, exec, s[8:9]
	s_cbranch_execnz .LBB0_513
